# merge GEMM phase: workgroups with bit3 of block id set start 8us late (2x s_sleep 127) so the HBM-bound gate-hook load bursts of the two halves interleave
# speedup vs baseline: 1.0219x; 1.0055x over previous
; __global__ void __launch_bounds__(NTHREADS, 2) fwd_kernel(Args A) {
;     ...
;         case 4: if (PMASK & 16) { pg8::Gemm g{(const bf16_t*)(ws + WS_Y), wl + WT_BR, Mx, DM, DM, 0, 0}; const bool coop = (ph_hi - ph_lo > 1);
;                   if (last) S.init(NLAT, DM, C.G, C.bid); else if (coop) S.init(NLAT, DM, C.G, C.bid, NCTX, 4); else S.init(MROWS, DM, C.G, C.bid);
;                   pg8::EpiMerge E{(const bf16_t*)(ws + WS_G), (bf16_t*)(ws + WS_MB), (float*)(ws + WS_PB)};
;                   pg8::gemm_phase<pg8::EpiMerge, true>(C.lds, C.tid, g, S, E);
.LBB0_242:
	v_readlane_b32 s100, v249, 56
	s_nop 3
	s_bitcmp1_b32 s100, 3
	s_cbranch_scc0 .Lmerge_nodelay
	s_sleep 127
	s_sleep 127

; __global__ void __launch_bounds__(NTHREADS, 2) fwd_kernel(Args A) {
	.amdhsa_kernel _Z10fwd_kernel4Args
		.amdhsa_group_segment_fixed_size 0
		.amdhsa_private_segment_fixed_size 0
		.amdhsa_kernarg_size 448
		.amdhsa_user_sgpr_count 2
		.amdhsa_user_sgpr_dispatch_ptr 0
		.amdhsa_user_sgpr_queue_ptr 0
		.amdhsa_user_sgpr_kernarg_segment_ptr 1
		.amdhsa_user_sgpr_dispatch_id 0
		.amdhsa_user_sgpr_kernarg_preload_length 0
		.amdhsa_user_sgpr_kernarg_preload_offset 0
		.amdhsa_user_sgpr_private_segment_size 0
		.amdhsa_uses_dynamic_stack 0
		.amdhsa_enable_private_segment 0
		.amdhsa_system_sgpr_workgroup_id_x 1
		.amdhsa_system_sgpr_workgroup_id_y 0
		.amdhsa_system_sgpr_workgroup_id_z 0
		.amdhsa_system_sgpr_workgroup_info 0
		.amdhsa_system_vgpr_workitem_id 2
		.amdhsa_next_free_vgpr 250
		.amdhsa_next_free_sgpr 101
		.amdhsa_accum_offset 252
		.amdhsa_reserve_vcc 1
		.amdhsa_float_round_mode_32 0
		.amdhsa_float_round_mode_16_64 0
		.amdhsa_float_denorm_mode_32 3
		.amdhsa_float_denorm_mode_16_64 3
		.amdhsa_dx10_clamp 1
		.amdhsa_ieee_mode 1
		.amdhsa_fp16_overflow 0
		.amdhsa_tg_split 0
		.amdhsa_exception_fp_ieee_invalid_op 0
		.amdhsa_exception_fp_denorm_src 0
		.amdhsa_exception_fp_ieee_div_zero 0
		.amdhsa_exception_fp_ieee_overflow 0
		.amdhsa_exception_fp_ieee_underflow 0
		.amdhsa_exception_fp_ieee_inexact 0
		.amdhsa_exception_int_div_zero 0
	.end_amdhsa_kernel

; __global__ void __launch_bounds__(NTHREADS, 2) fwd_kernel(Args A) {
amdhsa.kernels:
  - .agpr_count:     0
    .args:
      - .offset:         0
        .size:           192
        .value_kind:     by_value
      - .offset:         192
        .size:           4
        .value_kind:     hidden_block_count_x
      - .offset:         196
        .size:           4
        .value_kind:     hidden_block_count_y
      - .offset:         200
        .size:           4
        .value_kind:     hidden_block_count_z
      - .offset:         204
        .size:           2
        .value_kind:     hidden_group_size_x
      - .offset:         206
        .size:           2
        .value_kind:     hidden_group_size_y
      - .offset:         208
        .size:           2
        .value_kind:     hidden_group_size_z
      - .offset:         210
        .size:           2
        .value_kind:     hidden_remainder_x
      - .offset:         212
        .size:           2
        .value_kind:     hidden_remainder_y
      - .offset:         214
        .size:           2
        .value_kind:     hidden_remainder_z
      - .offset:         232
        .size:           8
        .value_kind:     hidden_global_offset_x
      - .offset:         240
        .size:           8
        .value_kind:     hidden_global_offset_y
      - .offset:         248
        .size:           8
        .value_kind:     hidden_global_offset_z
      - .offset:         256
        .size:           2
        .value_kind:     hidden_grid_dims
      - .offset:         280
        .size:           8
        .value_kind:     hidden_multigrid_sync_arg
      - .offset:         312
        .size:           4
        .value_kind:     hidden_dynamic_lds_size
    .group_segment_fixed_size: 0
    .kernarg_segment_align: 8
    .kernarg_segment_size: 448
    .language:       OpenCL C
    .language_version:
      - 2
      - 0
    .max_flat_workgroup_size: 512
    .name:           _Z10fwd_kernel4Args
    .private_segment_fixed_size: 0
    .sgpr_count:     107
    .sgpr_spill_count: 75
    .symbol:         _Z10fwd_kernel4Args.kd
    .uniform_work_group_size: 1
    .uses_dynamic_stack: false
    .vgpr_count:     250
    .vgpr_spill_count: 0
    .wavefront_size: 64
